# cache-policy hint: non-temporal (nt) on the in-projection tile's row stores (P is written once per layer and read only in the next phase)
# speedup vs baseline: 1.1231x; 1.0052x over previous
; DI void phaseA_tile(const Params& p0, int l, int ft, int mt, char* lds) {
;     ...
;     for (int i = 0; i < 16; ++i) {
;       const int idx = tid + NTHREADS * i;
;       const int row = idx >> 5, c = idx & 31;
;       if (c < nch) {
;         const u32x4 val = *(const u32x4*)(lds + row * 512 + ((c ^ (row & 31)) << 4));
;         *(u32x4*)(p.P + (size_t)(m0 + row) * INW + n0 + c * 8) = val;
;       }
;     }
.Lea_full:
	s_waitcnt lgkmcnt(15)
	global_store_dwordx4 v8, v[50:53], s[2:3] nt
	s_add_u32 s2, s2, 0x16000
	s_addc_u32 s3, s3, 0
	s_waitcnt lgkmcnt(14)
	global_store_dwordx4 v8, v[54:57], s[2:3] nt
	s_add_u32 s2, s2, 0x16000
	s_addc_u32 s3, s3, 0
	s_waitcnt lgkmcnt(13)
	global_store_dwordx4 v8, v[58:61], s[2:3] nt
	s_add_u32 s2, s2, 0x16000
	s_addc_u32 s3, s3, 0
	s_waitcnt lgkmcnt(12)
	global_store_dwordx4 v8, v[62:65], s[2:3] nt
	s_add_u32 s2, s2, 0x16000
	s_addc_u32 s3, s3, 0
	s_waitcnt lgkmcnt(11)
	global_store_dwordx4 v8, v[66:69], s[2:3] nt
	s_add_u32 s2, s2, 0x16000
	s_addc_u32 s3, s3, 0
	s_waitcnt lgkmcnt(10)
	global_store_dwordx4 v8, v[70:73], s[2:3] nt
	s_add_u32 s2, s2, 0x16000
	s_addc_u32 s3, s3, 0
	s_waitcnt lgkmcnt(9)
	global_store_dwordx4 v8, v[74:77], s[2:3] nt
	s_add_u32 s2, s2, 0x16000
	s_addc_u32 s3, s3, 0
	s_waitcnt lgkmcnt(8)
	global_store_dwordx4 v8, v[78:81], s[2:3] nt
	s_add_u32 s2, s2, 0x16000
	s_addc_u32 s3, s3, 0
	s_waitcnt lgkmcnt(7)
	global_store_dwordx4 v8, v[82:85], s[2:3] nt
	s_add_u32 s2, s2, 0x16000
	s_addc_u32 s3, s3, 0
	s_waitcnt lgkmcnt(6)
	global_store_dwordx4 v8, v[86:89], s[2:3] nt
	s_add_u32 s2, s2, 0x16000
	s_addc_u32 s3, s3, 0
	s_waitcnt lgkmcnt(5)
	global_store_dwordx4 v8, v[90:93], s[2:3] nt
	s_add_u32 s2, s2, 0x16000
	s_addc_u32 s3, s3, 0
	s_waitcnt lgkmcnt(4)
	global_store_dwordx4 v8, v[94:97], s[2:3] nt
	s_add_u32 s2, s2, 0x16000
	s_addc_u32 s3, s3, 0
	s_waitcnt lgkmcnt(3)
	global_store_dwordx4 v8, v[98:101], s[2:3] nt
	s_add_u32 s2, s2, 0x16000
	s_addc_u32 s3, s3, 0
	s_waitcnt lgkmcnt(2)
	global_store_dwordx4 v8, v[102:105], s[2:3] nt
	s_add_u32 s2, s2, 0x16000
	s_addc_u32 s3, s3, 0
	s_waitcnt lgkmcnt(1)
	global_store_dwordx4 v8, v[106:109], s[2:3] nt
	s_add_u32 s2, s2, 0x16000
	s_addc_u32 s3, s3, 0
	s_waitcnt lgkmcnt(0)
	global_store_dwordx4 v8, v[110:113], s[2:3] nt
	s_mov_b64 exec, -1
